# sample-sequence conv groups placed on attention-first workgroups only (vcu%16 in {0,1})
# speedup vs baseline: 1.0124x; 1.0124x over previous
.LBB0_498:
	v_mbcnt_lo_u32_b32 v0, -1, 0
	v_mbcnt_hi_u32_b32 v0, -1, v0
	s_mov_b64 s[14:15], s[96:97]
	v_add_u32_e32 v6, s73, v0
	s_load_dwordx4 s[16:19], s[14:15], 0xd8
	s_load_dwordx2 s[40:41], s[14:15], 0x20
	s_load_dwordx8 s[4:11], s[14:15], 0x78
	s_and_b32 s98, s92, 14
	s_xor_b32 s98, s98, 0
	s_or_b32 s98, s98, s93
	s_cmp_eq_u32 s98, 0
	s_cbranch_scc0 .Lsconv_pf_done
	s_waitcnt lgkmcnt(0)
	s_lshr_b32 s98, s92, 4
	s_lshl_b32 s98, s98, 1
	s_and_b32 s99, s92, 1
	s_or_b32 s98, s98, s99
	s_mul_i32 s98, s98, 0xf000
	s_add_u32 s98, s40, s98
	s_addc_u32 s99, s41, 0
	v_lshlrev_b32_e32 v249, 7, v0
	global_load_dword v252, v249, s[98:99]
	s_add_u32 s98, s98, 0x2000
	s_addc_u32 s99, s99, 0
	global_load_dword v252, v249, s[98:99]
	s_add_u32 s98, s98, 0x2000
	s_addc_u32 s99, s99, 0
	global_load_dword v252, v249, s[98:99]
	s_add_u32 s98, s98, 0x2000
	s_addc_u32 s99, s99, 0
	global_load_dword v252, v249, s[98:99]
	s_add_u32 s98, s98, 0x2000
	s_addc_u32 s99, s99, 0
	global_load_dword v252, v249, s[98:99]
	s_add_u32 s98, s98, 0x2000
	s_addc_u32 s99, s99, 0
	global_load_dword v252, v249, s[98:99]
	s_add_u32 s98, s98, 0x2000
	s_addc_u32 s99, s99, 0
	global_load_dword v252, v249, s[98:99]

.LBB0_513:
	s_and_b32 s4, s12, 0x77
	s_cmp_lg_u32 s4, 0x0
	s_cselect_b64 s[4:5], -1, 0
	s_bfe_u32 s14, s12, 0x10003
	s_lshr_b32 s12, s12, 7
	s_lshl_b32 s12, s12, 1
	s_or_b32 s12, s12, s14
	s_cmp_gt_i32 s12, 31
	s_cselect_b64 s[14:15], -1, 0
	s_or_b64 s[4:5], s[4:5], s[14:15]
	s_andn2_b64 vcc, exec, s[4:5]
	s_cbranch_vccz .LBB0_548
	v_mov_b32_e32 v111, 0
	s_add_i32 s4, s34, 63
	v_mov_b32_e32 v113, v111
	s_ashr_i32 s14, s4, 6
	v_lshl_add_u64 v[0:1], s[16:17], 0, v[112:113]
	s_mov_b64 s[4:5], 0x8178000
	v_lshl_add_u64 v[92:93], v[0:1], 0, s[4:5]
	s_mul_i32 s5, s12, 0xf000
	v_lshl_add_u64 v[88:89], s[6:7], 0, v[112:113]
	s_mul_hi_i32 s4, s12, 0xf000
	s_add_u32 s6, s16, s5
	s_addc_u32 s7, s17, s4
	s_add_u32 s6, s6, 0x8178800
	s_addc_u32 s7, s7, 0
	v_lshl_add_u64 v[94:95], s[8:9], 0, v[112:113]
	s_add_u32 s8, s40, s5
	v_add_u32_e32 v0, 0, v112
	v_lshl_add_u64 v[90:91], s[42:43], 0, v[110:111]
	v_lshl_add_u64 v[96:97], s[10:11], 0, v[112:113]
	v_lshl_add_u64 v[98:99], s[18:19], 0, v[110:111]
	s_mul_hi_i32 s15, s14, 0xf000
	s_mul_i32 s24, s14, 0xf000
	s_addc_u32 s9, s41, s4
	v_add_u32_e32 v134, 0x2000, v0
	s_mov_b32 s25, 0xffff0000
	s_mov_b64 s[10:11], 0x1000
	s_mov_b64 s[16:17], 0x1800
	s_mov_b64 s[40:41], 0x2000
	s_mov_b64 s[42:43], 0x2800
	v_mov_b32_e32 v135, 0x358637bd
	s_mov_b32 s26, 0xf800000
	v_mov_b32_e32 v136, 0x260
	s_movk_i32 s27, 0x7fff
	v_lshlrev_b32_e32 v110, 1, v114
	s_brev_b32 s28, 64
	s_mov_b32 s29, 0x2001000
	s_branch .LBB0_516

.LBB0_548:
	s_and_b32 s98, s92, 14
	s_cmp_eq_u32 s98, 0
	s_cbranch_scc0 .Lscopy_done
	s_cmp_eq_u32 s93, 0
	s_cbranch_scc1 .Lscopy_done
	s_load_dwordx2 s[80:81], s[96:97], 0x20
	s_load_dwordx2 s[100:101], s[96:97], 0xd8
	s_lshr_b32 s98, s92, 4
	s_lshl_b32 s98, s98, 1
	s_and_b32 s99, s92, 1
	s_or_b32 s98, s98, s99
	s_mul_i32 s98, s98, 30
	s_lshl_b32 s99, s93, 2
	s_add_i32 s98, s98, s99
	s_lshl_b32 s98, s98, 11
	v_mbcnt_lo_u32_b32 v253, -1, 0
	v_mbcnt_hi_u32_b32 v253, -1, v253
	v_lshlrev_b32_e32 v253, 5, v253
	s_waitcnt lgkmcnt(0)
	s_add_u32 s80, s80, s98
	s_addc_u32 s81, s81, 0
	s_add_u32 s100, s100, s98
	s_addc_u32 s101, s101, 0
	s_add_u32 s100, s100, 0x8176000
	s_addc_u32 s101, s101, 0
	global_load_dwordx4 v[236:239], v253, s[80:81]
	global_load_dwordx4 v[240:243], v253, s[80:81] offset:16
	global_load_dwordx4 v[244:247], v253, s[80:81] offset:2048
	global_load_dwordx4 v[228:231], v253, s[80:81] offset:2064
	s_waitcnt vmcnt(0)
	global_store_dwordx4 v253, v[236:239], s[100:101]
	global_store_dwordx4 v253, v[240:243], s[100:101] offset:16
	global_store_dwordx4 v253, v[244:247], s[100:101] offset:2048
	global_store_dwordx4 v253, v[228:231], s[100:101] offset:2064
	s_cmp_eq_u32 s93, 7
	s_cbranch_scc1 .Lscopy_done
	s_add_u32 s80, s80, 0x1000
	s_addc_u32 s81, s81, 0
	s_add_u32 s100, s100, 0x1000
	s_addc_u32 s101, s101, 0
	s_nop 1
	global_load_dwordx4 v[236:239], v253, s[80:81]
	global_load_dwordx4 v[240:243], v253, s[80:81] offset:16
	global_load_dwordx4 v[244:247], v253, s[80:81] offset:2048
	global_load_dwordx4 v[228:231], v253, s[80:81] offset:2064
	s_waitcnt vmcnt(0)
	global_store_dwordx4 v253, v[236:239], s[100:101]
	global_store_dwordx4 v253, v[240:243], s[100:101] offset:16
	global_store_dwordx4 v253, v[244:247], s[100:101] offset:2048
	global_store_dwordx4 v253, v[228:231], s[100:101] offset:2064
